# v46 + ffn1_out(L0) unit order staggered: odd workgroups (odd XCDs) run their context split-K unit first, so the two halves' epilogue bursts do not coincide
# baseline (speedup 1.0000x reference)
; #define PG8_WAIT_V(n) asm volatile("s_waitcnt vmcnt(" #n ")" ::: "memory")
;     __device__ __forceinline__ unsigned code(int i, unsigned& ko_) const {
;         const int L = i * lat.G + lat.c; if (L < nlat) return lat.code(i, ko_);
;         const int Lp = L - nlat; if (Lp >= nsp) { ko_ = 0u; return 0u; }
;         const int r = Lp / nks, ks = Lp % nks; ko_ = (unsigned)(((ks >> 1) * (t1 + t2) + (ks & 1) * t1) * 64);
;         return 0x80000000u | ((unsigned)ks << 24) | ((unsigned)((ks & 1) ? t2 : t1) << 16) | ((unsigned)(64 + (r & 3)) << 8) | (unsigned)(r >> 2);
; template <class Epi, class Sched, bool ALIGN_EPI = false, bool SP2 = false>
; __device__ __forceinline__ void gemm_phase(PG8_LAS unsigned char* lds, const Gemm g, const Sched& S, const Epi& E, const int wv) {
;     ...
;     Unit cur, nxt; int ui = 0;
;     ...
;     bool ok0_; cur.pm = 0; cur.pn = 0; cur.ko = 0; cur.nk = 4; cur.ks = 0; PG8_NEXT(0, cur, ok0_);
;     if (!ok0_) return;
;     f32x4 acc[2][2][4][2];
; #pragma unroll
;     for (int a = 0; a < 2; ++a)
; #pragma unroll
;         for (int b = 0; b < 2; ++b)
; #pragma unroll
;             for (int m = 0; m < 4; ++m)
; #pragma unroll
;                 for (int n = 0; n < 2; ++n) acc[a][b][m][n] = (f32x4){0.f, 0.f, 0.f, 0.f};
;     bf16x8 At[4][2], B0[2][2], B1[2][2];
;     const char* cA = (const char*)g.A + (size_t)cur.pm * tstepA + (size_t)cur.ko * 2; const char* cB = (const char*)g.Bt + (size_t)cur.pn * tstepB + (size_t)cur.ko * 2;
;     S.a_ready(cur);
;     if constexpr (SP2) {
;         PG8_STAGE(PG8_SB(0, 0), cB, voffB); PG8_STAGE(PG8_SB(0, 1), cB + hstepB, voffB); PG8_STAGE(PG8_SA(0, 0), cA, voffA); PG8_STAGE(PG8_SA(0, 1), cA + hstepA, voffA);
;         if (wr == 1) PG8_BAR;
;         PG8_WAIT_V(2); PG8_BAR;
;         PG8_STAGE(PG8_SB(1, 0), cB + kstep, voffB); PG8_STAGE(PG8_SA(1, 0), cA + kstep, voffA); PG8_STAGE(PG8_SB(1, 1), cB + hstepB + kstep, voffB);
;         PG8_WAIT_V(6); PG8_BAR;
;     } else {
;         PG8_STAGE(PG8_SB(0, 0), cB, voffB); PG8_STAGE(PG8_SA(0, 0), cA, voffA); PG8_STAGE(PG8_SB(0, 1), cB + hstepB, voffB); PG8_STAGE(PG8_SA(0, 1), cA + hstepA, voffA);
;         if (wr == 1) PG8_BAR;
;         PG8_WAIT_V(4); PG8_BAR;
;         PG8_STAGE(PG8_SB(1, 0), cB + kstep, voffB); PG8_STAGE(PG8_SA(1, 0), cA + kstep, voffA); PG8_STAGE(PG8_SB(1, 1), cB + hstepB + kstep, voffB);
;         PG8_WAIT_V(6); PG8_BAR;
;     }
.LBB0_320:
	s_or_b64 exec, exec, s[36:37]
	v_readlane_b32 s4, v254, 45
	v_readlane_b32 s5, v254, 46
	v_readlane_b32 s2, v254, 43
	s_xor_b64 s[6:7], s[4:5], -1
	s_mul_i32 s4, s2, 0x16800
	s_mov_b32 s5, s41
	v_writelane_b32 v254, s4, 56
	s_waitcnt lgkmcnt(0)
	s_barrier
	v_writelane_b32 v254, s5, 57
	v_writelane_b32 v254, s6, 58
	s_mov_b64 s[4:5], -1
	s_and_b64 vcc, exec, s[6:7]
	v_writelane_b32 v254, s7, 59
	s_cbranch_vccz .LBB0_373
	v_readlane_b32 s2, v254, 49
	v_readlane_b32 s4, v254, 30
	v_readlane_b32 s5, v254, 32
	s_nop 1
	v_writelane_b32 v255, s4, 16
	v_writelane_b32 v255, s5, 17
	s_bitcmp1_b32 s2, 0
	s_cbranch_scc0 .Lstg_a_first
	s_bfe_u32 s4, s2, 0x20001
	s_mul_i32 s4, s4, 22
	s_add_i32 s4, s4, 12
	s_lshl_b32 s4, s4, 6
	s_and_b32 s8, s2, 7
	s_lshl_b32 s8, s8, 24
	s_lshl_b32 s20, s2, 5
	s_and_b32 s20, s20, 0x300
	s_bfe_u32 s5, s2, 0x30005
	s_or_b32 s5, s5, s8
	s_or_b32 s5, s5, s20
	s_or_b32 s5, s5, 0x800a4000
	v_writelane_b32 v254, s4, 30
	v_writelane_b32 v254, s5, 32
.Lstg_a_first:
	s_nop 0
	v_readlane_b32 s2, v254, 32
	s_mov_b64 s[4:5], s[96:97]
	s_mov_b32 s20, s94
	s_mov_b32 s8, s94
	s_cmp_gt_i32 s2, -1
	v_mbcnt_lo_u32_b32 v0, -1, 0
	v_mbcnt_hi_u32_b32 v0, -1, v0
	s_cbranch_scc1 .LBB0_372
	s_load_dwordx2 s[6:7], s[4:5], 0xb8
	v_readlane_b32 s2, v254, 43
	s_mul_i32 s2, s2, 0x99c0000
	v_mov_b32_e32 v7, 1
	v_readlane_b32 s24, v254, 30
	s_waitcnt lgkmcnt(0)
	s_add_u32 s2, s6, s2
	s_addc_u32 s9, s7, 0
	s_add_u32 s42, s6, 0xd26f000
	s_addc_u32 s43, s7, 0
	s_add_u32 s44, s2, 0x2b20f000
	s_addc_u32 s45, s9, 0
	s_lshl_b32 s2, s8, 10
	v_lshl_add_u32 v1, v0, 4, s2
	v_ashrrev_i32_e32 v2, 31, v1
	v_lshrrev_b32_e32 v2, 22, v2
	v_add_u32_e32 v2, v1, v2
	v_ashrrev_i32_e32 v2, 10, v2
	v_mul_i32_i24_e32 v3, 0x400, v2
	v_sub_u32_e32 v3, v1, v3
	v_lshrrev_b32_e32 v4, 4, v3
	v_bitop3_b32 v3, v4, v3, 32 bitop3:0x6c
	v_ashrrev_i32_e32 v5, 31, v3
	v_lshrrev_b32_e32 v5, 26, v5
	v_add_u32_e32 v5, v3, v5
	v_lshlrev_b32_e32 v4, 3, v2
	v_ashrrev_i32_e32 v6, 6, v5
	v_and_b32_e32 v5, 0xc0, v5
	v_and_b32_e32 v4, -16, v4
	v_lshlrev_b32_e32 v2, 5, v2
	v_sub_u32_e32 v3, v3, v5
	v_add_u32_e32 v4, v6, v4
	v_and_b32_e32 v2, 32, v2
	v_ashrrev_i16_sdwa v3, v7, sext(v3) dst_sel:DWORD dst_unused:UNUSED_PAD src0_sel:DWORD src1_sel:BYTE_0
	v_add_u32_sdwa v2, v2, sext(v3) dst_sel:DWORD dst_unused:UNUSED_PAD src0_sel:DWORD src1_sel:WORD_0
	v_lshlrev_b32_e32 v3, 1, v4
	v_lshrrev_b32_e32 v5, 2, v4
	v_and_b32_e32 v6, 3, v6
	s_mov_b32 s2, 0x7fffe0
	v_and_b32_e32 v3, 24, v3
	v_and_b32_e32 v5, 4, v5
	v_and_or_b32 v6, v4, s2, v6
	v_or3_b32 v3, v6, v5, v3
	s_movk_i32 s8, 0x1600
	v_mul_lo_u32 v4, v4, s8
	v_mul_u32_u24_e32 v3, 0x1600, v3
	v_add_u32_e32 v1, 0x2000, v1
	v_add_lshl_u32 v208, v2, v4, 1
	v_add_lshl_u32 v209, v3, v2, 1
	v_ashrrev_i32_e32 v2, 31, v1
	v_lshrrev_b32_e32 v2, 22, v2
	v_add_u32_e32 v2, v1, v2
	v_ashrrev_i32_e32 v2, 10, v2
	v_mul_i32_i24_e32 v3, 0x400, v2
	v_sub_u32_e32 v1, v1, v3
	v_lshrrev_b32_e32 v3, 4, v1
	v_bitop3_b32 v1, v3, v1, 32 bitop3:0x6c
	v_ashrrev_i32_e32 v4, 31, v1
	v_lshrrev_b32_e32 v4, 26, v4
	v_add_u32_e32 v4, v1, v4
	v_ashrrev_i32_e32 v5, 6, v4
	v_and_b32_e32 v4, 0xffc0, v4
	v_lshlrev_b32_e32 v3, 3, v2
	v_sub_u32_e32 v1, v1, v4
	v_and_b32_e32 v3, -16, v3
	v_lshrrev_b16_e32 v4, 7, v1
	v_add_u32_e32 v3, v5, v3
	v_and_b32_e32 v4, 1, v4
	v_and_b32_e32 v5, 3, v5
	v_lshlrev_b32_e32 v2, 5, v2
	v_add_u16_e32 v1, v1, v4
	v_and_or_b32 v5, v3, s2, v5
	v_readlane_b32 s2, v254, 32
	v_readlane_b32 s25, v254, 31
	v_and_b32_e32 v2, 32, v2
	v_ashrrev_i16_sdwa v1, v7, sext(v1) dst_sel:DWORD dst_unused:UNUSED_PAD src0_sel:DWORD src1_sel:BYTE_0
	s_lshl_b32 s46, s20, 10
	s_and_b32 s96, s2, 0xff
	s_ashr_i32 s25, s24, 31
	v_add_u32_sdwa v1, v2, sext(v1) dst_sel:DWORD dst_unused:UNUSED_PAD src0_sel:DWORD src1_sel:WORD_0
	v_lshlrev_b32_e32 v2, 1, v3
	v_lshrrev_b32_e32 v4, 2, v3
	v_mul_lo_u32 v3, v3, s8
	s_ashr_i32 s22, s20, 2
	s_add_i32 s46, s46, 0
	s_bfe_u32 s33, s2, 0x80008
	s_lshl_b64 s[8:9], s[24:25], 1
	s_mul_i32 s10, s96, 0x2c0000
	s_add_u32 s10, s44, s10
	s_addc_u32 s11, s45, 0
	s_add_u32 s28, s10, s8
	s_mul_i32 s2, s33, 0x2c0000
	s_addc_u32 s29, s11, s9
	s_add_i32 s47, s46, 0x10000
	s_add_i32 s48, s46, 0x12000
	v_and_b32_e32 v2, 24, v2
	v_and_b32_e32 v4, 4, v4
	s_add_u32 s2, s42, s2
	v_or3_b32 v2, v5, v4, v2
	s_addc_u32 s10, s43, 0
	s_add_i32 s49, s46, 0x14000
	s_load_dwordx2 s[4:5], s[4:5], 0x30
	v_mul_u32_u24_e32 v2, 0x1600, v2
	s_mov_b32 m0, s47
	s_nop 0
	global_load_lds_dwordx4 v209, s[28:29]
	s_add_u32 s18, s28, 0x160000
	v_add_lshl_u32 v211, v2, v1, 1
	s_mov_b32 m0, s48
	s_nop 0
	global_load_lds_dwordx4 v211, s[28:29]
	s_addc_u32 s19, s29, 0
	s_add_i32 s50, s46, 0x16000
	s_mov_b32 m0, s49
	s_nop 0
	global_load_lds_dwordx4 v209, s[18:19]
	s_add_u32 s30, s2, s8
	s_mov_b32 m0, s50
	s_nop 0
	global_load_lds_dwordx4 v211, s[18:19]
	s_addc_u32 s31, s10, s9
	s_add_i32 s51, s46, 0x2000
	s_add_i32 s52, s46, 0x4000
	s_mov_b32 m0, s46
	s_nop 0
	global_load_lds_dwordx4 v208, s[30:31]
	s_add_u32 s8, s30, 0x160000
	v_add_lshl_u32 v210, v1, v3, 1
	s_mov_b32 m0, s51
	s_nop 0
	global_load_lds_dwordx4 v210, s[30:31]
	s_addc_u32 s9, s31, 0
	s_add_i32 s53, s46, 0x6000
	s_mov_b32 m0, s52
	s_nop 0
	global_load_lds_dwordx4 v208, s[8:9]
	s_cmp_eq_u32 s22, 1
	s_mov_b32 m0, s53
	s_nop 0
	global_load_lds_dwordx4 v210, s[8:9]
	s_cselect_b64 s[8:9], -1, 0
	v_writelane_b32 v254, s8, 60
	v_mov_b32_e32 v243, 1
	s_cmp_lg_u32 s22, 1
	v_writelane_b32 v254, s9, 61
	s_cbranch_scc1 .LBB0_324
	s_barrier

;     __device__ __forceinline__ unsigned code(int i, unsigned& ko_) const { Unit u; u.pm = 0; u.pn = 0; u.ko = 0; u.nk = 0; u.ks = 0; const bool ok = next(i, u); ko_ = (unsigned)u.ko; return ok ? (0x80000000u | ((unsigned)u.nk << 16) | ((unsigned)u.pm << 8) | (unsigned)u.pn) : 0u; }
;     __host__ __device__ __forceinline__ bool next(int i, Unit& u) const {
;         const long L = (long)i * G + c; if (L >= nwg) return false;
;         int wgid = (int)L; { const int q = nwg / NXCD, r = nwg % NXCD, xcd = wgid % NXCD, off = wgid / NXCD; wgid = (xcd < r ? xcd * (q + 1) : r * (q + 1) + (xcd - r) * q) + off; }
;         const int nig = WGM * nN, gid = wgid / nig, fm = gid * WGM, gsz = (nM - fm) < WGM ? (nM - fm) : WGM;
;         u.pm = fm + ((wgid % nig) % gsz); u.pn = (wgid % nig) / gsz; u.ko = 0; u.nk = nk; return true;
;     __device__ __forceinline__ unsigned code(int i, unsigned& ko_) const {
;         const int L = i * lat.G + lat.c; if (L < nlat) return lat.code(i, ko_);
;         const int Lp = L - nlat; if (Lp >= nsp) { ko_ = 0u; return 0u; }
;         const int r = Lp / nks, ks = Lp % nks; ko_ = (unsigned)(((ks >> 1) * (t1 + t2) + (ks & 1) * t1) * 64);
;         return 0x80000000u | ((unsigned)ks << 24) | ((unsigned)((ks & 1) ? t2 : t1) << 16) | ((unsigned)(64 + (r & 3)) << 8) | (unsigned)(r >> 2);
.LBB0_327:
	s_add_i32 s71, s71, 1
	s_mul_i32 s23, s71, s70
	v_readlane_b32 s6, v254, 49
	s_add_i32 s23, s23, s6
	s_and_b32 s7, s6, 1
	s_cmpk_lt_i32 s23, 0x300
	s_cselect_b32 s7, s7, 0
	s_lshl_b32 s7, s7, 9
	s_add_i32 s23, s23, s7
	s_cmpk_ge_i32 s23, 0x300
	s_cselect_b32 s7, s7, 0
	s_sub_i32 s23, s23, s7
	s_lshr_b32 s7, s7, 1
	s_sub_i32 s23, s23, s7
	v_readlane_b32 s7, v254, 50
	s_cmpk_gt_i32 s23, 0x1ff
	s_mov_b64 s[24:25], -1
	s_cbranch_scc0 .LBB0_331
	s_and_b32 s2, s23, 0x7fffff00
	s_mov_b32 s7, 0
	s_cmpk_lg_i32 s2, 0x200
	s_mov_b32 s6, 0
	s_cbranch_scc1 .LBB0_330
	s_bfe_u32 s6, s23, 0x20001
	s_and_b32 s7, s23, 1
	s_mul_i32 s6, s6, 22
	s_mul_i32 s8, s7, 12
	s_and_b32 s2, s23, 7
	s_add_i32 s6, s6, s8
	s_lshl_b32 s6, s6, 6
	s_lshl_b32 s2, s2, 24
	s_cmp_eq_u32 s7, 0
	s_mov_b32 s7, 0xc0000
	s_cselect_b32 s7, s7, 0xa0000
	s_lshl_b32 s8, s23, 5
	s_bfe_u32 s9, s23, 0x30005
	s_and_b32 s8, s8, 0x300
	s_or_b32 s2, s9, s2
	s_or_b32 s2, s2, s8
	s_or_b32 s2, s2, s7
	s_or_b32 s7, s2, 0x80004000

;     __host__ __device__ __forceinline__ bool next(int i, Unit& u) const {
;         const long L = (long)i * G + c; if (L >= nwg) return false;
;         int wgid = (int)L; { const int q = nwg / NXCD, r = nwg % NXCD, xcd = wgid % NXCD, off = wgid / NXCD; wgid = (xcd < r ? xcd * (q + 1) : r * (q + 1) + (xcd - r) * q) + off; }
;         const int nig = WGM * nN, gid = wgid / nig, fm = gid * WGM, gsz = (nM - fm) < WGM ? (nM - fm) : WGM;
;         u.pm = fm + ((wgid % nig) % gsz); u.pn = (wgid % nig) / gsz; u.ko = 0; u.nk = nk; return true;
.LBB0_331:
	s_andn2_b64 vcc, exec, s[24:25]
	s_cbranch_vccnz .LBB0_338
	s_mul_i32 s2, s71, s90
	s_mul_hi_u32 s6, s71, s70
	s_add_i32 s6, s6, s2
	s_mul_i32 s2, s71, s70
	v_readlane_b32 s8, v254, 49
	s_add_u32 s24, s2, s8
	v_readlane_b32 s2, v254, 52
	s_addc_u32 s25, s6, s2
	s_mov_b32 s24, s23
	s_mov_b32 s25, 0
	s_waitcnt lgkmcnt(0)
	v_mov_b64_e32 v[0:1], 0x1ff
	v_cmp_gt_i64_e32 vcc, s[24:25], v[0:1]
	s_mov_b32 s6, 0
	s_mov_b32 s7, 0
	v_readlane_b32 s9, v254, 50
	s_cbranch_vccnz .LBB0_338
	s_ashr_i32 s2, s24, 31
	s_lshr_b32 s2, s2, 29
	s_add_i32 s7, s24, s2
	s_and_b32 s2, s7, -8
	s_sub_i32 s23, s24, s2
	s_cmp_gt_i32 s23, -1
	s_mov_b64 s[24:25], -1
	s_cbranch_scc0 .LBB0_335
	s_lshl_b32 s26, s23, 6
	s_mov_b64 s[24:25], 0

; #define PG8_WAIT_V(n) asm volatile("s_waitcnt vmcnt(" #n ")" ::: "memory")
; #define PG8_BAR __builtin_amdgcn_s_barrier()
; template <class Epi, class Sched, bool ALIGN_EPI = false, bool SP2 = false>
; __device__ __forceinline__ void gemm_phase(PG8_LAS unsigned char* lds, const Gemm g, const Sched& S, const Epi& E, const int wv) {
;     ...
;         cur = nxt; cA = nA; cB = nB; ++ui;
;         if constexpr (ALIGN_EPI) { if (wr == 1) PG8_BAR; }
;     }
;     PG8_WAIT_V(0);
;     if constexpr (!ALIGN_EPI) { if (wr == 0) PG8_BAR; }
;     PG8_BAR;
.LBB0_371:
	v_readlane_b32 s96, v255, 16
	v_readlane_b32 s97, v255, 17
	s_nop 1
	v_writelane_b32 v254, s96, 30
	v_writelane_b32 v254, s97, 32
	s_waitcnt vmcnt(0)
	v_readlane_b32 s96, v254, 47
	v_readlane_b32 s97, v254, 48
	v_readlane_b32 s92, v254, 49
	v_readlane_b32 s90, v254, 52
	s_barrier
	v_readlane_b32 s93, v254, 50
